# phase A weight convert: bf16 results transposed through per-wave LDS staging so each global store instruction writes 8 full 128-byte lines instead of 64 partial 16-byte pieces
# speedup vs baseline: 1.0189x; 1.0063x over previous
.LBB0_20:
	s_or_b64 exec, exec, s[6:7]
	s_lshl_b32 s34, s3, 3
	v_lshrrev_b32_e32 v85, 6, v144
	v_add_u32_e32 v1, s34, v85
	s_movk_i32 s2, 0x2f00
	s_lshl_b32 s84, s26, 3
	v_cmp_gt_i32_e32 vcc, s2, v1
	v_lshlrev_b32_e32 v84, 2, v85
	s_and_saveexec_b64 s[6:7], vcc
	s_cbranch_execz .LBB0_39
	s_add_u32 s8, s22, 0x4800000
	s_addc_u32 s9, s23, 0
	s_add_u32 s10, s22, 0x1c00000
	s_addc_u32 s11, s23, 0
	s_add_u32 s12, s22, 0x1400000
	v_lshlrev_b32_e32 v2, 1, v85
	s_addc_u32 s13, s23, 0
	v_lshl_add_u32 v12, s3, 4, v2
	v_lshlrev_b32_e32 v2, 6, v85
	s_add_u32 s14, s22, 0x1000000
	v_lshl_add_u32 v13, s3, 9, v2
	v_lshlrev_b32_e32 v2, 5, v85
	v_and_b32_e32 v0, 63, v144
	s_addc_u32 s15, s23, 0
	v_mov_b32_e32 v3, 0
	s_lshl_b32 s2, s26, 4
	s_lshl_b32 s33, s26, 9
	v_lshl_add_u32 v14, s3, 5, v84
	s_lshl_b32 s35, s26, 5
	v_lshl_add_u32 v15, s3, 8, v2
	s_lshl_b32 s42, s26, 8
	s_mov_b64 s[16:17], 0
	v_lshrrev_b32_e32 v128, 3, v0
	v_and_b32_e32 v129, 7, v0
	v_lshlrev_b32_e32 v130, 13, v85
	v_add_u32_e32 v130, 0x10000, v130
	v_lshl_add_u32 v86, v0, 7, v130
	v_lshl_add_u32 v86, v129, 4, v86
	v_xor_b32_e32 v87, 16, v86
	v_xor_b32_e32 v88, 32, v86
	v_xor_b32_e32 v89, 48, v86
	v_xor_b32_e32 v90, 64, v86
	v_xor_b32_e32 v91, 0x50, v86
	v_xor_b32_e32 v92, 0x60, v86
	v_xor_b32_e32 v93, 0x70, v86
	v_xor_b32_e32 v131, v129, v128
	v_lshl_add_u32 v132, v128, 7, v130
	v_lshl_add_u32 v132, v131, 4, v132
	v_lshlrev_b32_e32 v129, 4, v129
	v_mov_b32_e32 v127, 0
	s_branch .LBB0_23
.LBB0_22:
	s_or_b64 exec, exec, s[28:29]
	v_mul_hi_u32_u24_e32 v17, v10, v2
	v_mul_u32_u24_e32 v16, v10, v2
	v_lshl_add_u64 v[8:9], v[16:17], 2, v[8:9]
	v_lshlrev_b32_e32 v16, 2, v0
	v_mov_b32_e32 v17, v3
	v_lshl_add_u64 v[8:9], v[8:9], 0, v[16:17]
	v_lshlrev_b64 v[10:11], 2, v[10:11]
	v_lshl_add_u64 v[16:17], v[8:9], 0, v[10:11]
	v_lshl_add_u64 v[18:19], v[16:17], 0, v[10:11]
	v_lshl_add_u64 v[20:21], v[18:19], 0, v[10:11]
	v_lshl_add_u64 v[22:23], v[20:21], 0, v[10:11]
	v_lshl_add_u64 v[24:25], v[22:23], 0, v[10:11]
	v_lshl_add_u64 v[26:27], v[24:25], 0, v[10:11]
	v_lshl_add_u64 v[28:29], v[26:27], 0, v[10:11]
	global_load_dword v30, v[8:9], off nt
	s_nop 0
	global_load_dword v16, v[16:17], off nt
	s_nop 0
	global_load_dword v17, v[18:19], off nt
	s_nop 0
	global_load_dword v18, v[20:21], off nt
	global_load_dword v19, v[22:23], off nt
	s_nop 0
	global_load_dword v20, v[24:25], off nt
	global_load_dword v21, v[26:27], off nt
	global_load_dword v22, v[28:29], off nt
	v_lshl_add_u64 v[8:9], v[28:29], 0, v[10:11]
	global_load_dword v23, v[8:9], off nt
	v_lshl_add_u64 v[8:9], v[8:9], 0, v[10:11]
	global_load_dword v24, v[8:9], off nt
	v_lshl_add_u64 v[8:9], v[8:9], 0, v[10:11]
	global_load_dword v25, v[8:9], off nt
	v_lshl_add_u64 v[8:9], v[8:9], 0, v[10:11]
	global_load_dword v26, v[8:9], off nt
	v_lshl_add_u64 v[8:9], v[8:9], 0, v[10:11]
	global_load_dword v27, v[8:9], off nt
	v_lshl_add_u64 v[8:9], v[8:9], 0, v[10:11]
	global_load_dword v28, v[8:9], off nt
	v_lshl_add_u64 v[8:9], v[8:9], 0, v[10:11]
	global_load_dword v29, v[8:9], off nt
	v_lshl_add_u64 v[8:9], v[8:9], 0, v[10:11]
	global_load_dword v31, v[8:9], off nt
	v_lshl_add_u64 v[8:9], v[8:9], 0, v[10:11]
	global_load_dword v32, v[8:9], off nt
	v_lshl_add_u64 v[8:9], v[8:9], 0, v[10:11]
	global_load_dword v33, v[8:9], off nt
	v_lshl_add_u64 v[8:9], v[8:9], 0, v[10:11]
	global_load_dword v34, v[8:9], off nt
	v_lshl_add_u64 v[8:9], v[8:9], 0, v[10:11]
	global_load_dword v35, v[8:9], off nt
	v_lshl_add_u64 v[8:9], v[8:9], 0, v[10:11]
	global_load_dword v36, v[8:9], off nt
	v_lshl_add_u64 v[8:9], v[8:9], 0, v[10:11]
	global_load_dword v37, v[8:9], off nt
	v_lshl_add_u64 v[8:9], v[8:9], 0, v[10:11]
	global_load_dword v38, v[8:9], off nt
	v_lshl_add_u64 v[8:9], v[8:9], 0, v[10:11]
	global_load_dword v39, v[8:9], off nt
	v_lshl_add_u64 v[8:9], v[8:9], 0, v[10:11]
	global_load_dword v40, v[8:9], off nt
	v_lshl_add_u64 v[8:9], v[8:9], 0, v[10:11]
	global_load_dword v41, v[8:9], off nt
	v_lshl_add_u64 v[8:9], v[8:9], 0, v[10:11]
	global_load_dword v42, v[8:9], off nt
	v_lshl_add_u64 v[8:9], v[8:9], 0, v[10:11]
	global_load_dword v43, v[8:9], off nt
	v_lshl_add_u64 v[8:9], v[8:9], 0, v[10:11]
	global_load_dword v44, v[8:9], off nt
	v_lshl_add_u64 v[8:9], v[8:9], 0, v[10:11]
	global_load_dword v45, v[8:9], off nt
	v_lshl_add_u64 v[8:9], v[8:9], 0, v[10:11]
	global_load_dword v46, v[8:9], off nt
	v_lshl_add_u64 v[8:9], v[8:9], 0, v[10:11]
	global_load_dword v47, v[8:9], off nt
	v_lshl_add_u64 v[8:9], v[8:9], 0, v[10:11]
	global_load_dword v48, v[8:9], off nt
	v_lshl_add_u64 v[8:9], v[8:9], 0, v[10:11]
	global_load_dword v49, v[8:9], off nt
	v_lshl_add_u64 v[8:9], v[8:9], 0, v[10:11]
	global_load_dword v50, v[8:9], off nt
	v_lshl_add_u64 v[8:9], v[8:9], 0, v[10:11]
	global_load_dword v51, v[8:9], off nt
	v_lshl_add_u64 v[8:9], v[8:9], 0, v[10:11]
	global_load_dword v52, v[8:9], off nt
	v_lshl_add_u64 v[8:9], v[8:9], 0, v[10:11]
	global_load_dword v53, v[8:9], off nt
	v_lshl_add_u64 v[8:9], v[8:9], 0, v[10:11]
	global_load_dword v54, v[8:9], off nt
	v_lshl_add_u64 v[8:9], v[8:9], 0, v[10:11]
	global_load_dword v55, v[8:9], off nt
	v_lshl_add_u64 v[8:9], v[8:9], 0, v[10:11]
	global_load_dword v56, v[8:9], off nt
	v_lshl_add_u64 v[8:9], v[8:9], 0, v[10:11]
	global_load_dword v57, v[8:9], off nt
	v_lshl_add_u64 v[8:9], v[8:9], 0, v[10:11]
	global_load_dword v58, v[8:9], off nt
	v_lshl_add_u64 v[8:9], v[8:9], 0, v[10:11]
	global_load_dword v59, v[8:9], off nt
	v_lshl_add_u64 v[8:9], v[8:9], 0, v[10:11]
	global_load_dword v60, v[8:9], off nt
	v_lshl_add_u64 v[8:9], v[8:9], 0, v[10:11]
	global_load_dword v61, v[8:9], off nt
	v_lshl_add_u64 v[8:9], v[8:9], 0, v[10:11]
	global_load_dword v62, v[8:9], off nt
	v_lshl_add_u64 v[8:9], v[8:9], 0, v[10:11]
	global_load_dword v63, v[8:9], off nt
	v_lshl_add_u64 v[8:9], v[8:9], 0, v[10:11]
	global_load_dword v64, v[8:9], off nt
	v_lshl_add_u64 v[8:9], v[8:9], 0, v[10:11]
	global_load_dword v65, v[8:9], off nt
	v_lshl_add_u64 v[8:9], v[8:9], 0, v[10:11]
	global_load_dword v66, v[8:9], off nt
	v_lshl_add_u64 v[8:9], v[8:9], 0, v[10:11]
	global_load_dword v67, v[8:9], off nt
	v_lshl_add_u64 v[8:9], v[8:9], 0, v[10:11]
	global_load_dword v68, v[8:9], off nt
	v_lshl_add_u64 v[8:9], v[8:9], 0, v[10:11]
	global_load_dword v69, v[8:9], off nt
	v_lshl_add_u64 v[8:9], v[8:9], 0, v[10:11]
	global_load_dword v70, v[8:9], off nt
	v_lshl_add_u64 v[8:9], v[8:9], 0, v[10:11]
	global_load_dword v71, v[8:9], off nt
	v_lshl_add_u64 v[8:9], v[8:9], 0, v[10:11]
	global_load_dword v72, v[8:9], off nt
	v_lshl_add_u64 v[8:9], v[8:9], 0, v[10:11]
	global_load_dword v73, v[8:9], off nt
	v_lshl_add_u64 v[8:9], v[8:9], 0, v[10:11]
	global_load_dword v74, v[8:9], off nt
	v_lshl_add_u64 v[8:9], v[8:9], 0, v[10:11]
	global_load_dword v75, v[8:9], off nt
	v_lshl_add_u64 v[8:9], v[8:9], 0, v[10:11]
	global_load_dword v76, v[8:9], off nt
	v_lshl_add_u64 v[8:9], v[8:9], 0, v[10:11]
	global_load_dword v77, v[8:9], off nt
	v_lshl_add_u64 v[8:9], v[8:9], 0, v[10:11]
	v_lshl_add_u64 v[10:11], v[8:9], 0, v[10:11]
	global_load_dword v78, v[8:9], off nt
	s_nop 0
	global_load_dword v10, v[10:11], off nt
	v_lshlrev_b32_e32 v126, 4, v6
	v_mul_u32_u24_e32 v6, v6, v128
	v_lshlrev_b32_e32 v6, 1, v6
	v_add_u32_e32 v6, v6, v129
	v_mov_b32_e32 v7, v3
	v_lshl_add_u64 v[8:9], v[4:5], 0, v[6:7]
	s_waitcnt vmcnt(62)
	v_cvt_pk_bf16_f32 v4, v30, v16
	s_waitcnt vmcnt(60)
	v_cvt_pk_bf16_f32 v5, v17, v18
	s_waitcnt vmcnt(58)
	v_cvt_pk_bf16_f32 v6, v19, v20
	s_waitcnt vmcnt(56)
	v_cvt_pk_bf16_f32 v7, v21, v22
	v_lshl_add_u64 v[8:9], v[2:3], 1, v[8:9]
	ds_write_b128 v86, v[4:7]
	v_add_u32_e32 v1, s84, v1
	s_movk_i32 s28, 0x2eff
	s_waitcnt vmcnt(54)
	v_cvt_pk_bf16_f32 v4, v23, v24
	s_waitcnt vmcnt(52)
	v_cvt_pk_bf16_f32 v5, v25, v26
	s_waitcnt vmcnt(50)
	v_cvt_pk_bf16_f32 v6, v27, v28
	s_waitcnt vmcnt(48)
	v_cvt_pk_bf16_f32 v7, v29, v31
	ds_write_b128 v87, v[4:7]
	v_cmp_lt_i32_e32 vcc, s28, v1
	v_add_u32_e32 v12, s2, v12
	s_waitcnt vmcnt(46)
	v_cvt_pk_bf16_f32 v4, v32, v33
	s_waitcnt vmcnt(44)
	v_cvt_pk_bf16_f32 v5, v34, v35
	s_waitcnt vmcnt(42)
	v_cvt_pk_bf16_f32 v6, v36, v37
	s_waitcnt vmcnt(40)
	v_cvt_pk_bf16_f32 v7, v38, v39
	ds_write_b128 v88, v[4:7]
	v_add_u32_e32 v13, s33, v13
	v_add_u32_e32 v14, s35, v14
	s_waitcnt vmcnt(38)
	v_cvt_pk_bf16_f32 v4, v40, v41
	s_waitcnt vmcnt(36)
	v_cvt_pk_bf16_f32 v5, v42, v43
	s_waitcnt vmcnt(34)
	v_cvt_pk_bf16_f32 v6, v44, v45
	s_waitcnt vmcnt(32)
	v_cvt_pk_bf16_f32 v7, v46, v47
	ds_write_b128 v89, v[4:7]
	s_or_b64 s[16:17], vcc, s[16:17]
	v_add_u32_e32 v15, s42, v15
	s_waitcnt vmcnt(30)
	v_cvt_pk_bf16_f32 v4, v48, v49
	s_waitcnt vmcnt(28)
	v_cvt_pk_bf16_f32 v5, v50, v51
	s_waitcnt vmcnt(26)
	v_cvt_pk_bf16_f32 v6, v52, v53
	s_waitcnt vmcnt(24)
	v_cvt_pk_bf16_f32 v7, v54, v55
	ds_write_b128 v90, v[4:7]
	s_waitcnt vmcnt(22)
	s_nop 0
	v_cvt_pk_bf16_f32 v4, v56, v57
	s_waitcnt vmcnt(20)
	v_cvt_pk_bf16_f32 v5, v58, v59
	s_waitcnt vmcnt(18)
	v_cvt_pk_bf16_f32 v6, v60, v61
	s_waitcnt vmcnt(16)
	v_cvt_pk_bf16_f32 v7, v62, v63
	ds_write_b128 v91, v[4:7]
	s_waitcnt vmcnt(14)
	s_nop 0
	v_cvt_pk_bf16_f32 v4, v64, v65
	s_waitcnt vmcnt(12)
	v_cvt_pk_bf16_f32 v5, v66, v67
	s_waitcnt vmcnt(10)
	v_cvt_pk_bf16_f32 v6, v68, v69
	s_waitcnt vmcnt(8)
	v_cvt_pk_bf16_f32 v7, v70, v71
	ds_write_b128 v92, v[4:7]
	s_waitcnt vmcnt(6)
	s_nop 0
	v_cvt_pk_bf16_f32 v4, v72, v73
	s_waitcnt vmcnt(4)
	v_cvt_pk_bf16_f32 v5, v74, v75
	s_waitcnt vmcnt(2)
	v_cvt_pk_bf16_f32 v6, v76, v77
	s_waitcnt vmcnt(0)
	v_cvt_pk_bf16_f32 v7, v78, v10
	ds_write_b128 v93, v[4:7]
	ds_read_b128 v[94:97], v132
	ds_read_b128 v[98:101], v132 offset:1024
	ds_read_b128 v[102:105], v132 offset:2048
	ds_read_b128 v[106:109], v132 offset:3072
	ds_read_b128 v[110:113], v132 offset:4096
	ds_read_b128 v[114:117], v132 offset:5120
	ds_read_b128 v[118:121], v132 offset:6144
	ds_read_b128 v[122:125], v132 offset:7168
	s_waitcnt lgkmcnt(7)
	global_store_dwordx4 v[8:9], v[94:97], off
	v_lshl_add_u64 v[8:9], v[8:9], 0, v[126:127]
	s_waitcnt lgkmcnt(6)
	global_store_dwordx4 v[8:9], v[98:101], off
	v_lshl_add_u64 v[8:9], v[8:9], 0, v[126:127]
	s_waitcnt lgkmcnt(5)
	global_store_dwordx4 v[8:9], v[102:105], off
	v_lshl_add_u64 v[8:9], v[8:9], 0, v[126:127]
	s_waitcnt lgkmcnt(4)
	global_store_dwordx4 v[8:9], v[106:109], off
	v_lshl_add_u64 v[8:9], v[8:9], 0, v[126:127]
	s_waitcnt lgkmcnt(3)
	global_store_dwordx4 v[8:9], v[110:113], off
	v_lshl_add_u64 v[8:9], v[8:9], 0, v[126:127]
	s_waitcnt lgkmcnt(2)
	global_store_dwordx4 v[8:9], v[114:117], off
	v_lshl_add_u64 v[8:9], v[8:9], 0, v[126:127]
	s_waitcnt lgkmcnt(1)
	global_store_dwordx4 v[8:9], v[118:121], off
	v_lshl_add_u64 v[8:9], v[8:9], 0, v[126:127]
	s_waitcnt lgkmcnt(0)
	global_store_dwordx4 v[8:9], v[122:125], off
	s_andn2_b64 exec, exec, s[16:17]
	s_cbranch_execz .LBB0_39
